# P3 K-loop touches the residual x tile (16 lines per wave per iteration) so epilogue x loads hit cache; on top of bias-in-LDS
# baseline (speedup 1.0000x reference)
.LBB0_485:
	s_ashr_i32 s0, s4, 3
	s_add_i32 s0, s3, s0
	s_ashr_i32 s3, s0, 31
	s_lshr_b32 s3, s3, 27
	s_add_i32 s3, s0, s3
	s_ashr_i32 s5, s3, 5
	s_andn2_b32 s3, s3, 31
	s_sub_i32 s3, s0, s3
	s_bfe_i32 s0, s3, 0x80000
	s_bfe_u32 s0, s0, 0x3000c
	s_add_i32 s14, s3, s0
	s_bfe_i32 s0, s14, 0x80000
	s_and_b32 s14, s14, 0xf8
	s_sub_i32 s3, s3, s14
	v_lshlrev_b32_e32 v0, 4, v201
	s_lshl_b32 s5, s5, 3
	s_sext_i32_i16 s0, s0
	s_sext_i32_i8 s3, s3
	s_lshr_b32 s1, s33, 6
	s_waitcnt lgkmcnt(0)
	v_and_b32_e32 v1, 32, v201
	s_waitcnt vmcnt(0)
	v_bfe_u32 v10, v201, 2, 4
	v_lshrrev_b32_e32 v2, 3, v201
	s_movk_i32 s4, 0x70
	v_add_u32_e32 v11, 0x2000, v0
	s_lshr_b32 s0, s0, 3
	s_add_i32 s14, s5, s3
	s_lshl_b32 s16, s14, 20
	s_lshl_b32 s17, s0, 10
	s_add_i32 s16, s16, s17
	v_lshrrev_b32_e32 v226, 6, v201
	v_bfe_u32 v227, v201, 3, 1
	v_lshl_or_b32 v226, v226, 1, v227
	v_and_b32_e32 v227, 7, v201
	v_lshlrev_b32_e32 v227, 7, v227
	v_lshl_or_b32 v226, v226, 12, v227
	v_add_u32_e32 v226, s16, v226
	v_bitop3_b32 v8, v0, v1, 48 bitop3:0x6c
	v_and_or_b32 v2, v2, s4, v10
	v_lshrrev_b32_e32 v0, 7, v11
	s_movk_i32 s4, 0xf0
	s_ashr_i32 s15, s14, 31
	s_bfe_i64 s[18:19], s[0:1], 0x100000
	v_and_or_b32 v0, v0, s4, v10
	s_lshr_b32 s4, s33, 8
	s_lshl_b32 s39, s1, 10
	s_lshl_b64 s[16:17], s[14:15], 20
	s_lshl_b64 s[18:19], s[18:19], 20
	v_and_b32_e32 v9, 64, v201
	s_add_u32 s30, s88, s18
	v_or_b32_e32 v1, v8, v9
	s_addc_u32 s31, s89, s19
	s_add_i32 s40, s39, 0
	v_lshl_or_b32 v128, v2, 12, v1
	s_add_i32 m0, s40, 0x10000
	v_lshl_or_b32 v130, v0, 12, v1
	global_load_lds_dwordx4 v128, s[30:31]
	s_add_i32 m0, s40, 0x12000
	s_add_u32 s18, s30, 0x80000
	global_load_lds_dwordx4 v130, s[30:31]
	s_addc_u32 s19, s31, 0
	s_add_i32 m0, s40, 0x14000
	v_mov_b32_e32 v129, 0
	global_load_lds_dwordx4 v128, s[18:19]
	s_add_i32 m0, s40, 0x16000
	s_add_u32 s16, s12, s16
	s_addc_u32 s17, s13, s17
	s_add_i32 s41, s40, 0x2000
	global_load_lds_dwordx4 v130, s[18:19]
	s_mov_b32 m0, s40
	s_add_u32 s18, s16, 0x80000
	global_load_lds_dwordx4 v128, s[16:17]
	s_mov_b32 m0, s41
	s_addc_u32 s19, s17, 0
	s_add_i32 s43, s40, 0x4000
	global_load_lds_dwordx4 v130, s[16:17]
	s_mov_b32 m0, s43
	s_add_i32 s48, s40, 0x6000
	global_load_lds_dwordx4 v128, s[18:19]
	s_mov_b32 m0, s48
	v_mov_b32_e32 v131, v129
	global_load_lds_dwordx4 v130, s[18:19]
	v_lshl_add_u64 v[6:7], s[30:31], 0, v[128:129]
	v_lshl_add_u64 v[4:5], s[30:31], 0, v[130:131]
	v_lshl_add_u64 v[2:3], s[16:17], 0, v[128:129]
	s_cmp_lg_u32 s4, 1
	v_lshl_add_u64 v[0:1], s[16:17], 0, v[130:131]
	s_cbranch_scc1 .LBB0_487
	s_barrier

.LBB0_495:
	v_add_u32_e32 v147, s53, v145
	ds_read_b128 v[148:151], v147
	ds_read_b128 v[152:155], v147 offset:1024
	ds_read_b128 v[156:159], v147 offset:2048
	ds_read_b128 v[160:163], v147 offset:3072
	v_add_u32_e32 v147, s54, v145
	s_add_u32 s34, s16, s30
	ds_read_b128 v[164:167], v147
	ds_read_b128 v[172:175], v147 offset:1024
	ds_read_b128 v[176:179], v147 offset:2048
	ds_read_b128 v[180:183], v147 offset:3072
	s_addc_u32 s35, s17, s31
	s_add_u32 s34, s34, 0x100
	s_addc_u32 s35, s35, 0
	s_add_u32 s59, s27, s30
	s_addc_u32 s60, s55, s31
	s_cmpk_eq_i32 s30, 0xf00
	s_cselect_b32 s37, s21, s35
	s_cselect_b32 s36, s23, s34
	s_cselect_b32 s35, s56, s60
	s_cselect_b32 s34, s57, s59
	v_lshl_add_u64 v[168:169], v[140:141], 0, s[30:31]
	s_add_i32 m0, s40, 0xc000
	ds_read_b128 v[184:187], v146
	ds_read_b128 v[188:191], v146 offset:1024
	ds_read_b128 v[192:195], v146 offset:2048
	ds_read_b128 v[196:199], v146 offset:3072
	ds_read_b128 v[202:205], v146 offset:4096
	ds_read_b128 v[206:209], v146 offset:5120
	ds_read_b128 v[210:213], v146 offset:6144
	ds_read_b128 v[214:217], v146 offset:7168
	global_load_lds_dwordx4 v[168:169], off
	v_lshl_add_u64 v[168:169], v[142:143], 0, s[30:31]
	s_add_i32 m0, s40, 0xe000
	s_nop 0
	global_load_lds_dwordx4 v[168:169], off
	s_waitcnt vmcnt(8)
	global_load_dword v227, v226, s[44:45]
	v_add_u32_e32 v226, 0x10000, v226
	s_waitcnt lgkmcnt(0)
	s_barrier
	s_setprio 1
	s_waitcnt lgkmcnt(0)
	v_mfma_f32_16x16x32_bf16 v[124:127], v[148:151], v[184:187], v[124:127]
	v_mfma_f32_16x16x32_bf16 v[120:123], v[156:159], v[184:187], v[120:123]
	v_mfma_f32_16x16x32_bf16 v[108:111], v[148:151], v[192:195], v[108:111]
	v_mfma_f32_16x16x32_bf16 v[104:107], v[156:159], v[192:195], v[104:107]
	v_mfma_f32_16x16x32_bf16 v[92:95], v[148:151], v[202:205], v[92:95]
	v_mfma_f32_16x16x32_bf16 v[88:91], v[156:159], v[202:205], v[88:91]
	v_mfma_f32_16x16x32_bf16 v[76:79], v[148:151], v[210:213], v[76:79]
	v_mfma_f32_16x16x32_bf16 v[72:75], v[156:159], v[210:213], v[72:75]
	v_mfma_f32_16x16x32_bf16 v[124:127], v[152:155], v[188:191], v[124:127]
	v_mfma_f32_16x16x32_bf16 v[120:123], v[160:163], v[188:191], v[120:123]
	v_mfma_f32_16x16x32_bf16 v[108:111], v[152:155], v[196:199], v[108:111]
	v_mfma_f32_16x16x32_bf16 v[104:107], v[160:163], v[196:199], v[104:107]
	v_mfma_f32_16x16x32_bf16 v[92:95], v[152:155], v[206:209], v[92:95]
	v_mfma_f32_16x16x32_bf16 v[88:91], v[160:163], v[206:209], v[88:91]
	v_mfma_f32_16x16x32_bf16 v[76:79], v[152:155], v[214:217], v[76:79]
	v_mfma_f32_16x16x32_bf16 v[72:75], v[160:163], v[214:217], v[72:75]
	s_setprio 0
	s_setprio 1
	v_mfma_f32_16x16x32_bf16 v[116:119], v[164:167], v[184:187], v[116:119]
	v_mfma_f32_16x16x32_bf16 v[112:115], v[176:179], v[184:187], v[112:115]
	v_mfma_f32_16x16x32_bf16 v[100:103], v[164:167], v[192:195], v[100:103]
	v_mfma_f32_16x16x32_bf16 v[96:99], v[176:179], v[192:195], v[96:99]
	v_mfma_f32_16x16x32_bf16 v[84:87], v[164:167], v[202:205], v[84:87]
	v_mfma_f32_16x16x32_bf16 v[80:83], v[176:179], v[202:205], v[80:83]
	v_mfma_f32_16x16x32_bf16 v[68:71], v[164:167], v[210:213], v[68:71]
	v_mfma_f32_16x16x32_bf16 v[64:67], v[176:179], v[210:213], v[64:67]
	v_mfma_f32_16x16x32_bf16 v[116:119], v[172:175], v[188:191], v[116:119]
	v_mfma_f32_16x16x32_bf16 v[112:115], v[180:183], v[188:191], v[112:115]
	v_mfma_f32_16x16x32_bf16 v[100:103], v[172:175], v[196:199], v[100:103]
	v_mfma_f32_16x16x32_bf16 v[96:99], v[180:183], v[196:199], v[96:99]
	v_mfma_f32_16x16x32_bf16 v[84:87], v[172:175], v[206:209], v[84:87]
	v_mfma_f32_16x16x32_bf16 v[80:83], v[180:183], v[206:209], v[80:83]
	v_mfma_f32_16x16x32_bf16 v[68:71], v[172:175], v[214:217], v[68:71]
	v_mfma_f32_16x16x32_bf16 v[64:67], v[180:183], v[214:217], v[64:67]
	s_setprio 0
	s_barrier
	s_add_i32 s59, s53, s39
	v_lshl_add_u64 v[168:169], s[34:35], 0, v[128:129]
	s_mov_b32 m0, s59
	ds_read_b128 v[184:187], v146 offset:16384
	ds_read_b128 v[188:191], v146 offset:17408
	ds_read_b128 v[192:195], v146 offset:18432
	ds_read_b128 v[196:199], v146 offset:19456
	ds_read_b128 v[202:205], v146 offset:20480
	ds_read_b128 v[206:209], v146 offset:21504
	ds_read_b128 v[210:213], v146 offset:22528
	ds_read_b128 v[214:217], v146 offset:23552
	global_load_lds_dwordx4 v[168:169], off
	s_add_i32 m0, s59, 0x2000
	s_add_u32 s60, s34, 0x80000
	v_lshl_add_u64 v[218:219], s[34:35], 0, v[130:131]
	s_addc_u32 s61, s35, 0
	s_add_i32 s59, s54, s39
	global_load_lds_dwordx4 v[218:219], off
	v_lshl_add_u64 v[220:221], s[60:61], 0, v[128:129]
	s_mov_b32 m0, s59
	v_lshl_add_u64 v[222:223], s[36:37], 0, v[130:131]
	global_load_lds_dwordx4 v[220:221], off
	v_lshl_add_u64 v[220:221], s[60:61], 0, v[130:131]
	s_add_i32 m0, s59, 0x2000
	s_nop 0
	global_load_lds_dwordx4 v[220:221], off
	v_lshl_add_u64 v[220:221], s[36:37], 0, v[128:129]
	s_mov_b32 m0, s40
	s_nop 0
	global_load_lds_dwordx4 v[220:221], off
	s_mov_b32 m0, s41
	s_nop 0
	global_load_lds_dwordx4 v[222:223], off
	s_waitcnt vmcnt(9)
	s_waitcnt lgkmcnt(0)
	s_barrier
	s_setprio 1
	s_waitcnt lgkmcnt(0)
	v_mfma_f32_16x16x32_bf16 v[60:63], v[148:151], v[184:187], v[60:63]
	v_mfma_f32_16x16x32_bf16 v[56:59], v[156:159], v[184:187], v[56:59]
	v_mfma_f32_16x16x32_bf16 v[44:47], v[148:151], v[192:195], v[44:47]
	v_mfma_f32_16x16x32_bf16 v[40:43], v[156:159], v[192:195], v[40:43]
	v_mfma_f32_16x16x32_bf16 v[28:31], v[148:151], v[202:205], v[28:31]
	v_mfma_f32_16x16x32_bf16 v[24:27], v[156:159], v[202:205], v[24:27]
	v_mfma_f32_16x16x32_bf16 v[12:15], v[148:151], v[210:213], v[12:15]
	v_mfma_f32_16x16x32_bf16 v[8:11], v[156:159], v[210:213], v[8:11]
	v_mfma_f32_16x16x32_bf16 v[60:63], v[152:155], v[188:191], v[60:63]
	v_mfma_f32_16x16x32_bf16 v[56:59], v[160:163], v[188:191], v[56:59]
	v_mfma_f32_16x16x32_bf16 v[44:47], v[152:155], v[196:199], v[44:47]
	v_mfma_f32_16x16x32_bf16 v[40:43], v[160:163], v[196:199], v[40:43]
	v_mfma_f32_16x16x32_bf16 v[28:31], v[152:155], v[206:209], v[28:31]
	v_mfma_f32_16x16x32_bf16 v[24:27], v[160:163], v[206:209], v[24:27]
	v_mfma_f32_16x16x32_bf16 v[12:15], v[152:155], v[214:217], v[12:15]
	v_mfma_f32_16x16x32_bf16 v[8:11], v[160:163], v[214:217], v[8:11]
	s_setprio 0
	s_setprio 1
	v_mfma_f32_16x16x32_bf16 v[52:55], v[164:167], v[184:187], v[52:55]
	v_mfma_f32_16x16x32_bf16 v[48:51], v[176:179], v[184:187], v[48:51]
	v_mfma_f32_16x16x32_bf16 v[36:39], v[164:167], v[192:195], v[36:39]
	v_mfma_f32_16x16x32_bf16 v[32:35], v[176:179], v[192:195], v[32:35]
	v_mfma_f32_16x16x32_bf16 v[20:23], v[164:167], v[202:205], v[20:23]
	v_mfma_f32_16x16x32_bf16 v[16:19], v[176:179], v[202:205], v[16:19]
	v_mfma_f32_16x16x32_bf16 v[4:7], v[164:167], v[210:213], v[4:7]
	v_mfma_f32_16x16x32_bf16 v[0:3], v[176:179], v[210:213], v[0:3]
	v_mfma_f32_16x16x32_bf16 v[52:55], v[172:175], v[188:191], v[52:55]
	v_mfma_f32_16x16x32_bf16 v[48:51], v[180:183], v[188:191], v[48:51]
	v_mfma_f32_16x16x32_bf16 v[36:39], v[172:175], v[196:199], v[36:39]
	v_mfma_f32_16x16x32_bf16 v[32:35], v[180:183], v[196:199], v[32:35]
	v_mfma_f32_16x16x32_bf16 v[20:23], v[172:175], v[206:209], v[20:23]
	v_mfma_f32_16x16x32_bf16 v[16:19], v[180:183], v[206:209], v[16:19]
	v_mfma_f32_16x16x32_bf16 v[4:7], v[172:175], v[214:217], v[4:7]
	v_mfma_f32_16x16x32_bf16 v[0:3], v[180:183], v[214:217], v[0:3]
	s_setprio 0
	s_barrier
	s_add_i32 s59, 0, 0x18000
	v_add_u32_e32 v147, s59, v145
	s_add_i32 s60, 0, 0x1c000
	ds_read_b128 v[148:151], v147
	ds_read_b128 v[152:155], v147 offset:1024
	ds_read_b128 v[156:159], v147 offset:2048
	ds_read_b128 v[160:163], v147 offset:3072
	v_add_u32_e32 v147, s60, v145
	ds_read_b128 v[164:167], v147
	ds_read_b128 v[172:175], v147 offset:1024
	ds_read_b128 v[176:179], v147 offset:2048
	ds_read_b128 v[180:183], v147 offset:3072
	s_add_u32 s36, s36, 0x80000
	s_addc_u32 s37, s37, 0
	s_mov_b32 m0, s43
	v_lshl_add_u64 v[224:225], s[36:37], 0, v[128:129]
	ds_read_b128 v[184:187], v146 offset:32768
	ds_read_b128 v[188:191], v146 offset:33792
	ds_read_b128 v[192:195], v146 offset:34816
	ds_read_b128 v[196:199], v146 offset:35840
	ds_read_b128 v[202:205], v146 offset:36864
	ds_read_b128 v[206:209], v146 offset:37888
	ds_read_b128 v[210:213], v146 offset:38912
	ds_read_b128 v[214:217], v146 offset:39936
	global_load_lds_dwordx4 v[224:225], off
	v_lshl_add_u64 v[224:225], s[36:37], 0, v[130:131]
	s_mov_b32 m0, s48
	s_nop 0
	global_load_lds_dwordx4 v[224:225], off
	s_waitcnt vmcnt(9)
	s_waitcnt lgkmcnt(0)
	s_barrier
	s_setprio 1
	s_waitcnt lgkmcnt(0)
	v_mfma_f32_16x16x32_bf16 v[124:127], v[148:151], v[184:187], v[124:127]
	v_mfma_f32_16x16x32_bf16 v[120:123], v[156:159], v[184:187], v[120:123]
	v_mfma_f32_16x16x32_bf16 v[108:111], v[148:151], v[192:195], v[108:111]
	v_mfma_f32_16x16x32_bf16 v[104:107], v[156:159], v[192:195], v[104:107]
	v_mfma_f32_16x16x32_bf16 v[92:95], v[148:151], v[202:205], v[92:95]
	v_mfma_f32_16x16x32_bf16 v[88:91], v[156:159], v[202:205], v[88:91]
	v_mfma_f32_16x16x32_bf16 v[76:79], v[148:151], v[210:213], v[76:79]
	v_mfma_f32_16x16x32_bf16 v[72:75], v[156:159], v[210:213], v[72:75]
	v_mfma_f32_16x16x32_bf16 v[124:127], v[152:155], v[188:191], v[124:127]
	v_mfma_f32_16x16x32_bf16 v[120:123], v[160:163], v[188:191], v[120:123]
	v_mfma_f32_16x16x32_bf16 v[108:111], v[152:155], v[196:199], v[108:111]
	v_mfma_f32_16x16x32_bf16 v[104:107], v[160:163], v[196:199], v[104:107]
	v_mfma_f32_16x16x32_bf16 v[92:95], v[152:155], v[206:209], v[92:95]
	v_mfma_f32_16x16x32_bf16 v[88:91], v[160:163], v[206:209], v[88:91]
	v_mfma_f32_16x16x32_bf16 v[76:79], v[152:155], v[214:217], v[76:79]
	v_mfma_f32_16x16x32_bf16 v[72:75], v[160:163], v[214:217], v[72:75]
	s_setprio 0
	s_setprio 1
	v_mfma_f32_16x16x32_bf16 v[116:119], v[164:167], v[184:187], v[116:119]
	v_mfma_f32_16x16x32_bf16 v[112:115], v[176:179], v[184:187], v[112:115]
	v_mfma_f32_16x16x32_bf16 v[100:103], v[164:167], v[192:195], v[100:103]
	v_mfma_f32_16x16x32_bf16 v[96:99], v[176:179], v[192:195], v[96:99]
	v_mfma_f32_16x16x32_bf16 v[84:87], v[164:167], v[202:205], v[84:87]
	v_mfma_f32_16x16x32_bf16 v[80:83], v[176:179], v[202:205], v[80:83]
	v_mfma_f32_16x16x32_bf16 v[68:71], v[164:167], v[210:213], v[68:71]
	v_mfma_f32_16x16x32_bf16 v[64:67], v[176:179], v[210:213], v[64:67]
	v_mfma_f32_16x16x32_bf16 v[116:119], v[172:175], v[188:191], v[116:119]
	v_mfma_f32_16x16x32_bf16 v[112:115], v[180:183], v[188:191], v[112:115]
	v_mfma_f32_16x16x32_bf16 v[100:103], v[172:175], v[196:199], v[100:103]
	v_mfma_f32_16x16x32_bf16 v[96:99], v[180:183], v[196:199], v[96:99]
	v_mfma_f32_16x16x32_bf16 v[84:87], v[172:175], v[206:209], v[84:87]
	v_mfma_f32_16x16x32_bf16 v[80:83], v[180:183], v[206:209], v[80:83]
	v_mfma_f32_16x16x32_bf16 v[68:71], v[172:175], v[214:217], v[68:71]
	v_mfma_f32_16x16x32_bf16 v[64:67], v[180:183], v[214:217], v[64:67]
	s_setprio 0
	s_barrier
	s_add_i32 s36, s59, s39
	v_lshl_add_u64 v[168:169], v[168:169], 0, s[18:19]
	s_mov_b32 m0, s36
	ds_read_b128 v[184:187], v146 offset:49152
	ds_read_b128 v[188:191], v146 offset:50176
	ds_read_b128 v[192:195], v146 offset:51200
	ds_read_b128 v[196:199], v146 offset:52224
	ds_read_b128 v[202:205], v146 offset:53248
	ds_read_b128 v[206:209], v146 offset:54272
	ds_read_b128 v[210:213], v146 offset:55296
	ds_read_b128 v[214:217], v146 offset:56320
	global_load_lds_dwordx4 v[168:169], off
	s_add_i32 m0, s36, 0x2000
	s_add_u32 s34, s34, 0x80080
	v_lshl_add_u64 v[168:169], v[218:219], 0, s[18:19]
	s_addc_u32 s35, s35, 0
	s_add_i32 s36, s60, s39
	global_load_lds_dwordx4 v[168:169], off
	v_lshl_add_u64 v[168:169], s[34:35], 0, v[128:129]
	s_mov_b32 m0, s36
	s_nop 0
	global_load_lds_dwordx4 v[168:169], off
	v_lshl_add_u64 v[168:169], s[34:35], 0, v[130:131]
	s_add_i32 m0, s36, 0x2000
	s_nop 0
	global_load_lds_dwordx4 v[168:169], off
	v_lshl_add_u64 v[168:169], v[220:221], 0, s[18:19]
	s_mov_b32 m0, s49
	s_nop 0
	global_load_lds_dwordx4 v[168:169], off
	v_lshl_add_u64 v[168:169], v[222:223], 0, s[18:19]
	s_mov_b32 m0, s50
	s_nop 0
	global_load_lds_dwordx4 v[168:169], off
	s_waitcnt vmcnt(8)
	s_waitcnt lgkmcnt(0)
	s_barrier
	s_setprio 1
	s_waitcnt lgkmcnt(0)
	v_mfma_f32_16x16x32_bf16 v[60:63], v[148:151], v[184:187], v[60:63]
	v_mfma_f32_16x16x32_bf16 v[56:59], v[156:159], v[184:187], v[56:59]
	v_mfma_f32_16x16x32_bf16 v[44:47], v[148:151], v[192:195], v[44:47]
	v_mfma_f32_16x16x32_bf16 v[40:43], v[156:159], v[192:195], v[40:43]
	v_mfma_f32_16x16x32_bf16 v[28:31], v[148:151], v[202:205], v[28:31]
	v_mfma_f32_16x16x32_bf16 v[24:27], v[156:159], v[202:205], v[24:27]
	v_mfma_f32_16x16x32_bf16 v[12:15], v[148:151], v[210:213], v[12:15]
	v_mfma_f32_16x16x32_bf16 v[8:11], v[156:159], v[210:213], v[8:11]
	v_mfma_f32_16x16x32_bf16 v[60:63], v[152:155], v[188:191], v[60:63]
	v_mfma_f32_16x16x32_bf16 v[56:59], v[160:163], v[188:191], v[56:59]
	v_mfma_f32_16x16x32_bf16 v[44:47], v[152:155], v[196:199], v[44:47]
	v_mfma_f32_16x16x32_bf16 v[40:43], v[160:163], v[196:199], v[40:43]
	v_mfma_f32_16x16x32_bf16 v[28:31], v[152:155], v[206:209], v[28:31]
	v_mfma_f32_16x16x32_bf16 v[24:27], v[160:163], v[206:209], v[24:27]
	v_mfma_f32_16x16x32_bf16 v[12:15], v[152:155], v[214:217], v[12:15]
	v_mfma_f32_16x16x32_bf16 v[8:11], v[160:163], v[214:217], v[8:11]
	s_setprio 0
	s_setprio 1
	v_mfma_f32_16x16x32_bf16 v[52:55], v[164:167], v[184:187], v[52:55]
	v_mfma_f32_16x16x32_bf16 v[48:51], v[176:179], v[184:187], v[48:51]
	v_mfma_f32_16x16x32_bf16 v[36:39], v[164:167], v[192:195], v[36:39]
	v_mfma_f32_16x16x32_bf16 v[32:35], v[176:179], v[192:195], v[32:35]
	v_mfma_f32_16x16x32_bf16 v[20:23], v[164:167], v[202:205], v[20:23]
	v_mfma_f32_16x16x32_bf16 v[16:19], v[176:179], v[202:205], v[16:19]
	v_mfma_f32_16x16x32_bf16 v[4:7], v[164:167], v[210:213], v[4:7]
	v_mfma_f32_16x16x32_bf16 v[0:3], v[176:179], v[210:213], v[0:3]
	v_mfma_f32_16x16x32_bf16 v[52:55], v[172:175], v[188:191], v[52:55]
	v_mfma_f32_16x16x32_bf16 v[48:51], v[180:183], v[188:191], v[48:51]
	v_mfma_f32_16x16x32_bf16 v[36:39], v[172:175], v[196:199], v[36:39]
	v_mfma_f32_16x16x32_bf16 v[32:35], v[180:183], v[196:199], v[32:35]
	v_mfma_f32_16x16x32_bf16 v[20:23], v[172:175], v[206:209], v[20:23]
	v_mfma_f32_16x16x32_bf16 v[16:19], v[180:183], v[206:209], v[16:19]
	v_mfma_f32_16x16x32_bf16 v[4:7], v[172:175], v[214:217], v[4:7]
	v_mfma_f32_16x16x32_bf16 v[0:3], v[180:183], v[214:217], v[0:3]
	s_setprio 0
	s_barrier
	s_add_i32 s58, s58, 2
	s_add_u32 s30, s30, 0x100
	s_addc_u32 s31, s31, 0
	s_cmp_gt_u32 s58, 29
	s_cbranch_scc0 .LBB0_495
	s_add_u32 s30, s27, 0xffffff00
	s_addc_u32 s31, s55, -1
	s_andn2_b64 vcc, exec, s[4:5]
	s_cbranch_vccnz .LBB0_498
	v_mov_b32_e32 v0, 0
	s_mov_b32 s51, s20
	s_mov_b32 s14, s22
	s_mov_b64 s[16:17], s[28:29]
	s_mov_b32 s52, s26
	v_mov_b32_e32 v1, v0
	v_mov_b32_e32 v2, v0
	v_mov_b32_e32 v3, v0
	v_mov_b32_e32 v4, v0
	v_mov_b32_e32 v5, v0
	v_mov_b32_e32 v6, v0
	v_mov_b32_e32 v7, v0
	v_mov_b32_e32 v16, v0
	v_mov_b32_e32 v17, v0
	v_mov_b32_e32 v18, v0
	v_mov_b32_e32 v19, v0
	v_mov_b32_e32 v20, v0
	v_mov_b32_e32 v21, v0
	v_mov_b32_e32 v22, v0
	v_mov_b32_e32 v23, v0
	v_mov_b32_e32 v32, v0
	v_mov_b32_e32 v33, v0
	v_mov_b32_e32 v34, v0
	v_mov_b32_e32 v35, v0
	v_mov_b32_e32 v36, v0
	v_mov_b32_e32 v37, v0
	v_mov_b32_e32 v38, v0
	v_mov_b32_e32 v39, v0
	v_mov_b32_e32 v48, v0
	v_mov_b32_e32 v49, v0
	v_mov_b32_e32 v50, v0
	v_mov_b32_e32 v51, v0
	v_mov_b32_e32 v52, v0
	v_mov_b32_e32 v53, v0
	v_mov_b32_e32 v54, v0
	v_mov_b32_e32 v55, v0
	v_mov_b32_e32 v8, v0
	v_mov_b32_e32 v9, v0
	v_mov_b32_e32 v10, v0
	v_mov_b32_e32 v11, v0
	v_mov_b32_e32 v12, v0
	v_mov_b32_e32 v13, v0
	v_mov_b32_e32 v14, v0
	v_mov_b32_e32 v15, v0
	v_mov_b32_e32 v24, v0
	v_mov_b32_e32 v25, v0
	v_mov_b32_e32 v26, v0
	v_mov_b32_e32 v27, v0
	v_mov_b32_e32 v28, v0
	v_mov_b32_e32 v29, v0
	v_mov_b32_e32 v30, v0
	v_mov_b32_e32 v31, v0
	v_mov_b32_e32 v40, v0
	v_mov_b32_e32 v41, v0
	v_mov_b32_e32 v42, v0
	v_mov_b32_e32 v43, v0
	v_mov_b32_e32 v44, v0
	v_mov_b32_e32 v45, v0
	v_mov_b32_e32 v46, v0
	v_mov_b32_e32 v47, v0
	v_mov_b32_e32 v56, v0
	v_mov_b32_e32 v57, v0
	v_mov_b32_e32 v58, v0
	v_mov_b32_e32 v59, v0
	v_mov_b32_e32 v60, v0
	v_mov_b32_e32 v61, v0
	v_mov_b32_e32 v62, v0
	v_mov_b32_e32 v63, v0
	v_mov_b32_e32 v64, v0
	v_mov_b32_e32 v65, v0
	v_mov_b32_e32 v66, v0
	v_mov_b32_e32 v67, v0
	v_mov_b32_e32 v68, v0
	v_mov_b32_e32 v69, v0
	v_mov_b32_e32 v70, v0
	v_mov_b32_e32 v71, v0
	v_mov_b32_e32 v80, v0
	v_mov_b32_e32 v81, v0
	v_mov_b32_e32 v82, v0
	v_mov_b32_e32 v83, v0
	v_mov_b32_e32 v84, v0
	v_mov_b32_e32 v85, v0
	v_mov_b32_e32 v86, v0
	v_mov_b32_e32 v87, v0
	v_mov_b32_e32 v96, v0
	v_mov_b32_e32 v97, v0
	v_mov_b32_e32 v98, v0
	v_mov_b32_e32 v99, v0
	v_mov_b32_e32 v100, v0
	v_mov_b32_e32 v101, v0
	v_mov_b32_e32 v102, v0
	v_mov_b32_e32 v103, v0
	v_mov_b32_e32 v112, v0
	v_mov_b32_e32 v113, v0
	v_mov_b32_e32 v114, v0
	v_mov_b32_e32 v115, v0
	v_mov_b32_e32 v116, v0
	v_mov_b32_e32 v117, v0
	v_mov_b32_e32 v118, v0
	v_mov_b32_e32 v119, v0
	v_mov_b32_e32 v72, v0
	v_mov_b32_e32 v73, v0
	v_mov_b32_e32 v74, v0
	v_mov_b32_e32 v75, v0
	v_mov_b32_e32 v76, v0
	v_mov_b32_e32 v77, v0
	v_mov_b32_e32 v78, v0
	v_mov_b32_e32 v79, v0
	v_mov_b32_e32 v88, v0
	v_mov_b32_e32 v89, v0
	v_mov_b32_e32 v90, v0
	v_mov_b32_e32 v91, v0
	v_mov_b32_e32 v92, v0
	v_mov_b32_e32 v93, v0
	v_mov_b32_e32 v94, v0
	v_mov_b32_e32 v95, v0
	v_mov_b32_e32 v104, v0
	v_mov_b32_e32 v105, v0
	v_mov_b32_e32 v106, v0
	v_mov_b32_e32 v107, v0
	v_mov_b32_e32 v108, v0
	v_mov_b32_e32 v109, v0
	v_mov_b32_e32 v110, v0
	v_mov_b32_e32 v111, v0
	v_mov_b32_e32 v120, v0
	v_mov_b32_e32 v121, v0
	v_mov_b32_e32 v122, v0
	v_mov_b32_e32 v123, v0
	v_mov_b32_e32 v124, v0
	v_mov_b32_e32 v125, v0
	v_mov_b32_e32 v126, v0
	v_mov_b32_e32 v127, v0
	s_andn2_b64 vcc, exec, s[0:1]
	s_cbranch_vccnz .LBB0_499
	s_branch .LBB0_500
